# v22 + MLA attention skips the per-tile row max / rescale test when the QK-norm gains bound the scores (runtime guard, original path kept as fallback)
# speedup vs baseline: 1.0075x; 1.0046x over previous
.LBB0_1467:
	s_cmp_lt_i32 s94, 6
	s_cselect_b64 s[0:1], -1, 0
	s_cmp_gt_i32 s95, 5
	s_cselect_b64 s[4:5], -1, 0
	s_and_b64 s[0:1], s[0:1], s[4:5]
	s_andn2_b64 vcc, exec, s[0:1]
	s_cbranch_vccnz .LBB0_1608
	v_readlane_b32 s100, v244, 0
	v_readlane_b32 s101, v244, 1
	s_sub_u32 s100, s100, 0xd8
	s_subb_u32 s101, s101, 0
	s_load_dwordx8 s[12:19], s[100:101], 0x58
	v_and_b32_e32 v1, 63, v0
	v_and_b32_e32 v2, 31, v0
	v_lshlrev_b32_e32 v1, 2, v1
	v_lshlrev_b32_e32 v2, 2, v2
	s_waitcnt lgkmcnt(0)
	global_load_dword v3, v1, s[12:13]
	global_load_dword v4, v2, s[14:15]
	global_load_dword v5, v1, s[16:17]
	global_load_dword v6, v2, s[18:19]
	s_waitcnt vmcnt(0)
	v_max3_f32 v3, |v3|, |v4|, |v5|
	v_max_f32_e64 v3, v3, |v6|
	v_mov_b32_e32 v4, 0x3fb50000
	v_cmp_gt_f32_e32 vcc, v4, v3
	s_cmp_eq_u64 vcc, exec
	s_cselect_b32 s101, 1, 0
	s_abs_i32 s0, s33
	v_cvt_f32_u32_e32 v1, s0
	s_sub_i32 s5, 0, s0
	s_add_i32 s1, s33, 0x3ff
	s_xor_b32 s4, s1, s33
	v_rcp_iflag_f32_e32 v1, v1
	s_abs_i32 s1, s1
	s_ashr_i32 s4, s4, 31
	v_mul_f32_e32 v1, 0x4f7ffffe, v1
	v_cvt_u32_f32_e32 v1, v1
	s_nop 0
	v_readfirstlane_b32 s6, v1
	s_mul_i32 s5, s5, s6
	s_mul_hi_u32 s5, s6, s5
	s_add_i32 s6, s6, s5
	s_mul_hi_u32 s5, s1, s6
	s_mul_i32 s6, s5, s0
	s_sub_i32 s1, s1, s6
	s_add_i32 s7, s5, 1
	s_sub_i32 s6, s1, s0
	s_cmp_ge_u32 s1, s0
	s_cselect_b32 s5, s7, s5
	s_cselect_b32 s1, s6, s1
	s_add_i32 s6, s5, 1
	s_cmp_ge_u32 s1, s0
	s_cselect_b32 s0, s6, s5
	s_xor_b32 s0, s0, s4
	s_sub_i32 s1, s0, s4
	s_mul_i32 s0, s1, s87
	s_sub_i32 s4, 0x400, s0
	s_min_i32 s1, s4, s1
	s_cmpk_lt_i32 s0, 0x400
	s_cselect_b32 s28, s1, 0
	s_cmp_lt_i32 s28, 1
	s_cbranch_scc1 .LBB0_1497
	s_lshl_b32 s1, s87, 2
	s_andn2_b32 s1, s1, 63
	s_and_b32 s4, s87, 15
	s_or_b32 s1, s1, s4
	s_cmpk_eq_i32 s33, 0x100
	s_cselect_b64 s[6:7], -1, 0
	s_and_b64 s[4:5], s[6:7], exec
	s_cselect_b32 s29, s1, s0
	s_ashr_i32 s8, s29, 6
	s_bfe_u32 s13, s29, 0x30003
	s_ashr_i32 s9, s8, 31
	s_lshl_b32 s0, s13, 6
	s_lshl_b64 s[18:19], s[8:9], 20
	s_lshl_b64 s[4:5], s[8:9], 21
	s_add_u32 s1, s10, s4
	s_addc_u32 s4, s11, s5
	s_lshl_b32 s5, s13, 7
	v_mov_b32_e32 v3, v0
	s_add_u32 s24, s1, s5
	s_addc_u32 s25, s4, 0
	v_readfirstlane_b32 s14, v3
	s_ashr_i32 s22, s14, 6
	s_lshl_b32 s1, s22, 4
	v_bfe_u32 v5, v3, 2, 4
	v_and_or_b32 v2, s1, 48, v5
	s_ashr_i32 s1, s14, 3
	s_andn2_b32 s1, s1, 31
	v_bfe_u32 v6, v3, 4, 2
	v_lshl_add_u32 v8, v2, 9, s1
	s_lshl_b32 s1, s22, 9
	s_lshl_b32 s15, s22, 10
	v_bitop3_b32 v1, v6, v3, 3 bitop3:0x78
	s_cmp_lg_u32 0, -1
	v_lshlrev_b32_e32 v2, 3, v1
	s_cselect_b32 s4, 0, 0
	v_or_b32_e32 v1, v8, v2
	s_add_i32 s38, s15, s4
	v_lshlrev_b32_e32 v1, 1, v1
	v_lshlrev_b32_e32 v9, 5, v5
	s_add_i32 s39, s38, 0x2000
	s_nop 4
	s_mov_b32 s12, m0
	s_mov_b32 m0, s38
	s_nop 0
	global_load_lds_dwordx4 v1, s[24:25]
	s_mov_b32 m0, s12
	v_or3_b32 v9, s1, v9, v2
	s_cmp_lt_i32 s22, 4
	v_readlane_b32 s16, v244, 46
	v_and_b32_e32 v4, 63, v3
	v_and_b32_e32 v7, 3, v3
	v_lshlrev_b32_e32 v180, 1, v9
	s_mov_b32 s1, 0
	s_cselect_b64 s[4:5], -1, 0
	s_cmp_gt_i32 s22, 3
	v_readlane_b32 s17, v244, 47
	s_cbranch_scc1 .LBB0_1471
	s_lshl_b64 s[24:25], s[8:9], 17
	s_add_u32 s24, s16, s24
	s_addc_u32 s25, s17, s25
	s_nop 4
	s_mov_b32 s12, m0
	s_mov_b32 m0, s39
	s_nop 0
	global_load_lds_dwordx4 v180, s[24:25]
	s_mov_b32 m0, s12

.LBB0_1478:
	s_add_u32 s26, s0, s24
	s_addc_u32 s27, s53, s25
	s_lshl_b32 s51, s57, 13
	s_add_i32 s58, s51, s43
	s_nop 4
	s_mov_b32 s59, m0
	s_mov_b32 m0, s58
	s_nop 0
	global_load_lds_dwordx4 v181, s[26:27]
	s_mov_b32 m0, s59
	s_waitcnt lgkmcnt(11)
	v_mfma_f32_32x32x16_bf16 v[66:81], v[82:85], v[98:101], v[50:65]
	s_lshl_b32 s58, s49, 13
	s_waitcnt lgkmcnt(10)
	v_mfma_f32_32x32x16_bf16 v[82:97], v[158:161], v[98:101], v[50:65]
	v_add_u32_e32 v158, s58, v183
	s_waitcnt lgkmcnt(9)
	v_mfma_f32_32x32x16_bf16 v[66:81], v[162:165], v[106:109], v[66:81]
	s_waitcnt lgkmcnt(8)
	v_mfma_f32_32x32x16_bf16 v[82:97], v[150:153], v[106:109], v[82:97]
	s_waitcnt lgkmcnt(7)
	v_mfma_f32_32x32x16_bf16 v[66:81], v[146:149], v[102:105], v[66:81]
	s_waitcnt lgkmcnt(6)
	v_mfma_f32_32x32x16_bf16 v[82:97], v[142:145], v[102:105], v[82:97]
	s_waitcnt lgkmcnt(5)
	v_mfma_f32_32x32x16_bf16 v[66:81], v[138:141], v[114:117], v[66:81]
	ds_read_b64_tr_b16 v[150:151], v158 offset:24576
	ds_read_b64_tr_b16 v[152:153], v158 offset:25088
	ds_read_b64_tr_b16 v[146:147], v158 offset:25600
	ds_read_b64_tr_b16 v[148:149], v158 offset:26112
	ds_read_b64_tr_b16 v[142:143], v158 offset:26624
	ds_read_b64_tr_b16 v[144:145], v158 offset:27136
	ds_read_b64_tr_b16 v[138:139], v158 offset:27648
	ds_read_b64_tr_b16 v[140:141], v158 offset:28160
	s_waitcnt lgkmcnt(12)
	v_mfma_f32_32x32x16_bf16 v[82:97], v[134:137], v[114:117], v[82:97]
	s_waitcnt lgkmcnt(11)
	v_mfma_f32_32x32x16_bf16 v[66:81], v[130:133], v[110:113], v[66:81]
	s_waitcnt lgkmcnt(10)
	v_mfma_f32_32x32x16_bf16 v[82:97], v[126:129], v[110:113], v[82:97]
	s_waitcnt lgkmcnt(9)
	v_mfma_f32_32x32x16_bf16 v[66:81], v[122:125], v[118:121], v[66:81]
	ds_read_b64_tr_b16 v[134:135], v158 offset:28672
	ds_read_b64_tr_b16 v[136:137], v158 offset:29184
	ds_read_b64_tr_b16 v[130:131], v158 offset:29696
	ds_read_b64_tr_b16 v[132:133], v158 offset:30208
	ds_read_b64_tr_b16 v[126:127], v158 offset:30720
	ds_read_b64_tr_b16 v[128:129], v158 offset:31232
	ds_read_b64_tr_b16 v[122:123], v158 offset:31744
	ds_read_b64_tr_b16 v[124:125], v158 offset:32256
	s_waitcnt lgkmcnt(14)
	v_mfma_f32_32x32x16_bf16 v[82:97], v[154:157], v[118:121], v[82:97]
	s_cmp_lg_u32 s101, 0
	s_cbranch_scc1 .Lmla2_fast
	s_nop 1
	v_max_f32_e32 v154, v67, v67
	v_max_f32_e32 v155, v66, v66
	v_max_f32_e32 v154, v155, v154
	s_nop 6
	v_max3_f32 v155, v68, v69, v83
	v_max3_f32 v154, v154, v82, v84
	v_max3_f32 v154, v154, v85, v70
	v_max3_f32 v155, v155, v72, v73
	v_max3_f32 v154, v154, v71, v86
	v_max3_f32 v155, v155, v88, v89
	v_max3_f32 v154, v154, v87, v74
	v_max3_f32 v155, v155, v76, v77
	v_max3_f32 v154, v154, v75, v90
	v_max3_f32 v155, v155, v92, v93
	v_max3_f32 v154, v154, v91, v78
	v_max3_f32 v155, v155, v80, v81
	v_max3_f32 v154, v154, v79, v94
	v_max3_f32 v155, v155, v96, v97
	v_max3_f32 v154, v154, v95, v155
	v_mov_b32_e32 v155, v154
	s_nop 1
	v_permlane32_swap_b32_e32 v154, v155
	v_max_f32_e32 v155, v155, v155
	v_max_f32_e32 v154, v154, v154
	v_max_f32_e32 v154, v154, v155
	v_cmp_lt_f32_e32 vcc, s47, v154
	s_cbranch_vccz .LBB0_1482
	v_max_f32_e32 v50, v154, v154
	v_max_f32_e32 v154, 0, v50
	v_exp_f32_e64 v155, -v154
	v_add_f32_e32 v171, v171, v154
	v_xor_b32_e32 v50, 0x80000000, v171
	v_mov_b32_e32 v51, v50
	v_mov_b32_e32 v52, v50
	v_mov_b32_e32 v53, v50
	v_mov_b32_e32 v54, v50
	v_mov_b32_e32 v55, v50
	v_mov_b32_e32 v56, v50
	v_mov_b32_e32 v57, v50
	v_mov_b32_e32 v58, v50
	v_mov_b32_e32 v59, v50
	v_mov_b32_e32 v60, v50
	v_mov_b32_e32 v61, v50
	v_mov_b32_e32 v62, v50
	v_mov_b32_e32 v63, v50
	v_mov_b32_e32 v64, v50
	v_mov_b32_e32 v65, v50
	s_and_saveexec_b64 s[26:27], s[6:7]
	ds_write_b32 v186, v155 offset:40960
	s_or_b64 exec, exec, s[26:27]
	v_add_u32_e32 v164, s42, v187
	ds_read_b128 v[156:159], v164 offset:41024
	ds_read_b128 v[160:163], v164 offset:41056
	ds_read_b128 v[196:199], v164 offset:40960
	ds_read_b128 v[200:203], v164 offset:40992
	v_pk_add_f32 v[66:67], v[66:67], v[154:155] op_sel_hi:[1,0] neg_lo:[0,1] neg_hi:[0,1]
	v_pk_add_f32 v[82:83], v[82:83], v[154:155] op_sel_hi:[1,0] neg_lo:[0,1] neg_hi:[0,1]
	v_pk_add_f32 v[68:69], v[68:69], v[154:155] op_sel_hi:[1,0] neg_lo:[0,1] neg_hi:[0,1]
	v_pk_add_f32 v[84:85], v[84:85], v[154:155] op_sel_hi:[1,0] neg_lo:[0,1] neg_hi:[0,1]
	v_pk_add_f32 v[70:71], v[70:71], v[154:155] op_sel_hi:[1,0] neg_lo:[0,1] neg_hi:[0,1]
	v_pk_add_f32 v[86:87], v[86:87], v[154:155] op_sel_hi:[1,0] neg_lo:[0,1] neg_hi:[0,1]
	v_pk_add_f32 v[72:73], v[72:73], v[154:155] op_sel_hi:[1,0] neg_lo:[0,1] neg_hi:[0,1]
	v_pk_add_f32 v[88:89], v[88:89], v[154:155] op_sel_hi:[1,0] neg_lo:[0,1] neg_hi:[0,1]
	v_pk_add_f32 v[74:75], v[74:75], v[154:155] op_sel_hi:[1,0] neg_lo:[0,1] neg_hi:[0,1]
	v_pk_add_f32 v[90:91], v[90:91], v[154:155] op_sel_hi:[1,0] neg_lo:[0,1] neg_hi:[0,1]
	v_pk_add_f32 v[76:77], v[76:77], v[154:155] op_sel_hi:[1,0] neg_lo:[0,1] neg_hi:[0,1]
	v_pk_add_f32 v[92:93], v[92:93], v[154:155] op_sel_hi:[1,0] neg_lo:[0,1] neg_hi:[0,1]
	v_pk_add_f32 v[78:79], v[78:79], v[154:155] op_sel_hi:[1,0] neg_lo:[0,1] neg_hi:[0,1]
	v_pk_add_f32 v[94:95], v[94:95], v[154:155] op_sel_hi:[1,0] neg_lo:[0,1] neg_hi:[0,1]
	v_pk_add_f32 v[80:81], v[80:81], v[154:155] op_sel_hi:[1,0] neg_lo:[0,1] neg_hi:[0,1]
	v_pk_add_f32 v[96:97], v[96:97], v[154:155] op_sel_hi:[1,0] neg_lo:[0,1] neg_hi:[0,1]
	v_mul_f32_e32 v173, v173, v155
	s_waitcnt lgkmcnt(2)
	v_pk_mul_f32 v[30:31], v[30:31], v[160:161]
	v_pk_mul_f32 v[26:27], v[26:27], v[156:157]
	s_waitcnt lgkmcnt(0)
	v_pk_mul_f32 v[22:23], v[22:23], v[200:201]
	v_pk_mul_f32 v[32:33], v[32:33], v[162:163]
	v_pk_mul_f32 v[28:29], v[28:29], v[158:159]
	v_pk_mul_f32 v[24:25], v[24:25], v[202:203]
	v_pk_mul_f32 v[20:21], v[20:21], v[198:199]
	v_pk_mul_f32 v[18:19], v[18:19], v[196:197]
	v_pk_mul_f32 v[46:47], v[46:47], v[160:161]
	v_pk_mul_f32 v[42:43], v[42:43], v[156:157]
	v_pk_mul_f32 v[38:39], v[38:39], v[200:201]
	v_pk_mul_f32 v[48:49], v[48:49], v[162:163]
	v_pk_mul_f32 v[44:45], v[44:45], v[158:159]
	v_pk_mul_f32 v[40:41], v[40:41], v[202:203]
	v_pk_mul_f32 v[36:37], v[36:37], v[198:199]
	v_pk_mul_f32 v[34:35], v[34:35], v[196:197]
.Lmla2_fast:
	s_nop 3

.LBB0_1488:
	s_waitcnt lgkmcnt(11)
	v_mfma_f32_32x32x16_bf16 v[66:81], v[150:153], v[98:101], v[50:65]
	s_waitcnt lgkmcnt(10)
	v_mfma_f32_32x32x16_bf16 v[50:65], v[142:145], v[98:101], v[50:65]
	s_waitcnt lgkmcnt(9)
	v_mfma_f32_32x32x16_bf16 v[66:81], v[146:149], v[106:109], v[66:81]
	s_waitcnt lgkmcnt(8)
	v_mfma_f32_32x32x16_bf16 v[50:65], v[138:141], v[106:109], v[50:65]
	s_waitcnt lgkmcnt(7)
	v_mfma_f32_32x32x16_bf16 v[66:81], v[134:137], v[102:105], v[66:81]
	s_waitcnt lgkmcnt(6)
	v_mfma_f32_32x32x16_bf16 v[50:65], v[130:133], v[102:105], v[50:65]
	s_waitcnt lgkmcnt(5)
	v_mfma_f32_32x32x16_bf16 v[66:81], v[126:129], v[114:117], v[66:81]
	s_waitcnt lgkmcnt(4)
	v_mfma_f32_32x32x16_bf16 v[50:65], v[122:125], v[114:117], v[50:65]
	s_waitcnt lgkmcnt(3)
	v_mfma_f32_32x32x16_bf16 v[66:81], v[94:97], v[110:113], v[66:81]
	v_add_u32_e32 v94, s51, v183
	ds_read_b64_tr_b16 v[150:151], v94 offset:24576
	ds_read_b64_tr_b16 v[152:153], v94 offset:25088
	ds_read_b64_tr_b16 v[146:147], v94 offset:25600
	ds_read_b64_tr_b16 v[148:149], v94 offset:26112
	ds_read_b64_tr_b16 v[142:143], v94 offset:26624
	ds_read_b64_tr_b16 v[144:145], v94 offset:27136
	ds_read_b64_tr_b16 v[138:139], v94 offset:27648
	ds_read_b64_tr_b16 v[140:141], v94 offset:28160
	ds_read_b64_tr_b16 v[134:135], v94 offset:28672
	ds_read_b64_tr_b16 v[136:137], v94 offset:29184
	ds_read_b64_tr_b16 v[130:131], v94 offset:29696
	ds_read_b64_tr_b16 v[132:133], v94 offset:30208
	ds_read_b64_tr_b16 v[126:127], v94 offset:30720
	ds_read_b64_tr_b16 v[128:129], v94 offset:31232
	ds_read_b64_tr_b16 v[122:123], v94 offset:31744
	ds_read_b64_tr_b16 v[124:125], v94 offset:32256
	s_waitcnt lgkmcnt(14)
	v_mfma_f32_32x32x16_bf16 v[50:65], v[90:93], v[110:113], v[50:65]
	v_mfma_f32_32x32x16_bf16 v[66:81], v[86:89], v[118:121], v[66:81]
	v_mfma_f32_32x32x16_bf16 v[50:65], v[82:85], v[118:121], v[50:65]
	s_cmp_lg_u32 s101, 0
	s_cbranch_scc1 .Lmla3_fast
	s_nop 10
	v_max_f32_e32 v82, v67, v67
	v_max_f32_e32 v83, v66, v66
	v_max_f32_e32 v82, v83, v82
	v_max3_f32 v83, v68, v69, v51
	v_max3_f32 v82, v82, v50, v52
	v_max3_f32 v82, v82, v53, v70
	v_max3_f32 v83, v83, v72, v73
	v_max3_f32 v82, v82, v71, v54
	v_max3_f32 v83, v83, v56, v57
	v_max3_f32 v82, v82, v55, v74
	v_max3_f32 v83, v83, v76, v77
	v_max3_f32 v82, v82, v75, v58
	v_max3_f32 v83, v83, v60, v61
	v_max3_f32 v82, v82, v59, v78
	v_max3_f32 v83, v83, v80, v81
	v_max3_f32 v82, v82, v79, v62
	v_max3_f32 v83, v83, v64, v65
	v_max3_f32 v82, v82, v63, v83
	v_mov_b32_e32 v83, v82
	s_nop 1
	v_permlane32_swap_b32_e32 v82, v83
	v_max_f32_e32 v83, v83, v83
	v_max_f32_e32 v82, v82, v82
	v_max_f32_e32 v82, v82, v83
	v_cmp_lt_f32_e32 vcc, s47, v82
	s_cbranch_vccz .LBB0_1492
	v_max_f32_e32 v82, v82, v82
	v_max_f32_e32 v154, 0, v82
	v_exp_f32_e64 v155, -v154
	v_add_f32_e32 v82, v171, v154
	v_xor_b32_e32 v82, 0x80000000, v82
	v_mov_b32_e32 v83, v82
	v_mov_b32_e32 v84, v82
	v_mov_b32_e32 v85, v82
	v_mov_b32_e32 v86, v82
	v_mov_b32_e32 v87, v82
	v_mov_b32_e32 v88, v82
	v_mov_b32_e32 v89, v82
	v_mov_b32_e32 v90, v82
	v_mov_b32_e32 v91, v82
	v_mov_b32_e32 v92, v82
	v_mov_b32_e32 v93, v82
	v_mov_b32_e32 v94, v82
	v_mov_b32_e32 v95, v82
	v_mov_b32_e32 v96, v82
	v_mov_b32_e32 v97, v82
	s_and_saveexec_b64 s[8:9], s[6:7]
	ds_write_b32 v186, v155 offset:40960
	s_or_b64 exec, exec, s[8:9]
	v_add_u32_e32 v94, s42, v187
	ds_read_b128 v[82:85], v94 offset:41024
	ds_read_b128 v[86:89], v94 offset:41056
	ds_read_b128 v[90:93], v94 offset:40960
	ds_read_b128 v[94:97], v94 offset:40992
	v_pk_add_f32 v[66:67], v[66:67], v[154:155] op_sel_hi:[1,0] neg_lo:[0,1] neg_hi:[0,1]
	v_pk_add_f32 v[50:51], v[50:51], v[154:155] op_sel_hi:[1,0] neg_lo:[0,1] neg_hi:[0,1]
	v_pk_add_f32 v[68:69], v[68:69], v[154:155] op_sel_hi:[1,0] neg_lo:[0,1] neg_hi:[0,1]
	v_pk_add_f32 v[52:53], v[52:53], v[154:155] op_sel_hi:[1,0] neg_lo:[0,1] neg_hi:[0,1]
	v_pk_add_f32 v[70:71], v[70:71], v[154:155] op_sel_hi:[1,0] neg_lo:[0,1] neg_hi:[0,1]
	v_pk_add_f32 v[54:55], v[54:55], v[154:155] op_sel_hi:[1,0] neg_lo:[0,1] neg_hi:[0,1]
	v_pk_add_f32 v[72:73], v[72:73], v[154:155] op_sel_hi:[1,0] neg_lo:[0,1] neg_hi:[0,1]
	v_pk_add_f32 v[56:57], v[56:57], v[154:155] op_sel_hi:[1,0] neg_lo:[0,1] neg_hi:[0,1]
	v_pk_add_f32 v[74:75], v[74:75], v[154:155] op_sel_hi:[1,0] neg_lo:[0,1] neg_hi:[0,1]
	v_pk_add_f32 v[58:59], v[58:59], v[154:155] op_sel_hi:[1,0] neg_lo:[0,1] neg_hi:[0,1]
	v_pk_add_f32 v[76:77], v[76:77], v[154:155] op_sel_hi:[1,0] neg_lo:[0,1] neg_hi:[0,1]
	v_pk_add_f32 v[60:61], v[60:61], v[154:155] op_sel_hi:[1,0] neg_lo:[0,1] neg_hi:[0,1]
	v_pk_add_f32 v[78:79], v[78:79], v[154:155] op_sel_hi:[1,0] neg_lo:[0,1] neg_hi:[0,1]
	v_pk_add_f32 v[62:63], v[62:63], v[154:155] op_sel_hi:[1,0] neg_lo:[0,1] neg_hi:[0,1]
	v_pk_add_f32 v[80:81], v[80:81], v[154:155] op_sel_hi:[1,0] neg_lo:[0,1] neg_hi:[0,1]
	v_pk_add_f32 v[64:65], v[64:65], v[154:155] op_sel_hi:[1,0] neg_lo:[0,1] neg_hi:[0,1]
	v_mul_f32_e32 v173, v173, v155
	s_waitcnt lgkmcnt(2)
	v_pk_mul_f32 v[30:31], v[30:31], v[86:87]
	v_pk_mul_f32 v[26:27], v[26:27], v[82:83]
	s_waitcnt lgkmcnt(0)
	v_pk_mul_f32 v[22:23], v[22:23], v[94:95]
	v_pk_mul_f32 v[32:33], v[32:33], v[88:89]
	v_pk_mul_f32 v[28:29], v[28:29], v[84:85]
	v_pk_mul_f32 v[24:25], v[24:25], v[96:97]
	v_pk_mul_f32 v[20:21], v[20:21], v[92:93]
	v_pk_mul_f32 v[18:19], v[18:19], v[90:91]
	v_pk_mul_f32 v[46:47], v[46:47], v[86:87]
	v_pk_mul_f32 v[42:43], v[42:43], v[82:83]
	v_pk_mul_f32 v[38:39], v[38:39], v[94:95]
	v_pk_mul_f32 v[48:49], v[48:49], v[88:89]
	v_pk_mul_f32 v[44:45], v[44:45], v[84:85]
	v_pk_mul_f32 v[40:41], v[40:41], v[96:97]
	v_pk_mul_f32 v[36:37], v[36:37], v[92:93]
	v_pk_mul_f32 v[34:35], v[34:35], v[90:91]
.Lmla3_fast:
	s_nop 9
